# early L1 invalidate in grid barriers + GEMM priority flips deleted + one static s_setprio 1 for waves 4-7 at kernel entry
# speedup vs baseline: 1.0081x; 1.0006x over previous
; #define LAS __attribute__((address_space(3)))
; __global__ void __launch_bounds__(512, 2) fwd_megakernel(Params P) {
;     extern __shared__ __attribute__((aligned(16))) unsigned char lds_raw[];
;     LAS unsigned char* lds = (LAS unsigned char*)lds_raw;
;     cg::grid_group grid = cg::this_grid();
;     const int tid = threadIdx.x, lane = tid & 63, wave = __builtin_amdgcn_readfirstlane(tid >> 6);
;     const int G = gridDim.x, c = blockIdx.x;
;     const int gw = c * 8 + wave, ngw = G * 8;
;     LAS float* scr = (LAS float*)(lds + wave * 16384);
;     if (tid < 4) ((LAS unsigned*)(lds + LDS_CTL + 64))[tid] = 0u;
;     __syncthreads();
_Z14fwd_megakernel6Params:
	s_add_u32 s8, s0, 0xe8
	v_and_b32_e32 v196, 0x3ff, v0
	s_addc_u32 s9, s1, 0
	v_readfirstlane_b32 s3, v196
	s_nop 3
	s_cmp_lt_u32 s3, 0x100
	s_cbranch_scc1 .Lprio_young_done
	s_setprio 1
.Lprio_young_done:
	v_cmp_gt_u32_e32 vcc, 4, v196
	s_and_saveexec_b64 s[4:5], vcc
	v_lshl_add_u32 v1, v196, 2, 0
	v_add_u32_e32 v1, 0x23040, v1
	v_mov_b32_e32 v2, 0
	ds_write_b32 v1, v2
	s_or_b64 exec, exec, s[4:5]
	s_load_dwordx2 s[54:55], s[0:1], 0xe8
	s_cmp_eq_u32 s2, 0
	s_cselect_b64 s[6:7], -1, 0
	s_cmp_lg_u32 s2, 0
	s_mov_b32 s10, 0
	s_waitcnt lgkmcnt(0)
	s_barrier
	s_cbranch_scc1 .LBB0_10
	s_mov_b64 s[4:5], s[0:1]
	s_load_dwordx2 s[4:5], s[4:5], 0xe0
	v_sub_u32_e32 v1, 0xd7f, v196
	v_lshrrev_b32_e32 v2, 9, v1
	v_add_u32_e32 v1, 2, v2
	v_add_u32_e32 v197, 0x200, v196
	s_waitcnt lgkmcnt(0)
	s_add_u32 s12, s4, 0x4000
	v_and_b32_e32 v3, 14, v1
	s_addc_u32 s13, s5, 0
	v_mov_b32_e32 v1, v2
	s_mov_b64 s[14:15], 0
	s_mov_b32 s11, 1
	v_mov_b32_e32 v5, 0
	s_mov_b32 s16, s10
	v_mov_b64_e32 v[6:7], v[196:197]
	s_branch .LBB0_5
